# mla_row phase: the two 64-lane butterfly sums via DPP (quad_perm, row_half_mirror, row_mirror) + permlane16/32 swap instead of 6 ds_bpermute round trips each (same pairing, bit-identical)
# speedup vs baseline: 1.0025x; 1.0025x over previous
.LBB0_376:
	s_or_b64 exec, exec, s[2:3]
	v_lshl_add_u64 v[12:13], s[14:15], 0, v[30:31]
	global_load_dwordx4 v[12:15], v[12:13], off
	v_lshl_add_u64 v[50:51], s[14:15], 0, v[34:35]
	global_load_dword v49, v[50:51], off
	s_lshr_b32 s0, s12, 6
	v_mov_b32_e32 v52, s12
	v_mov_b32_e32 v53, s0
	v_cndmask_b32_e64 v52, v52, v53, s[8:9]
	v_lshlrev_b32_e32 v52, 4, v52
	s_movk_i32 s0, 0x3f0
	v_and_or_b32 v52, v52, s0, v42
	v_lshlrev_b32_e32 v52, 3, v52
	global_load_dwordx2 v[54:55], v52, s[16:17]
	s_waitcnt vmcnt(0)
	v_mul_f32_e32 v43, v21, v21
	v_mul_f32_e32 v44, v23, v23
	v_fmac_f32_e32 v43, v20, v20
	v_fmac_f32_e32 v44, v22, v22
	v_add_f32_e32 v43, v43, v44
	v_mul_f32_e32 v44, v17, v17
	v_mul_f32_e32 v45, v19, v19
	v_fmac_f32_e32 v44, v16, v16
	v_fmac_f32_e32 v45, v18, v18
	v_add_f32_e32 v44, v44, v45
	v_add_f32_e32 v43, v44, v43
	s_nop 1
	v_add_f32_dpp v43, v43, v43 quad_perm:[1,0,3,2] row_mask:0xf bank_mask:0xf
	s_nop 1
	v_add_f32_dpp v43, v43, v43 quad_perm:[2,3,0,1] row_mask:0xf bank_mask:0xf
	s_nop 1
	v_add_f32_dpp v43, v43, v43 row_half_mirror row_mask:0xf bank_mask:0xf
	s_nop 1
	v_add_f32_dpp v43, v43, v43 row_mirror row_mask:0xf bank_mask:0xf
	v_mov_b32_e32 v44, v43
	s_nop 1
	v_permlane16_swap_b32_e32 v43, v44
	v_add_f32_e32 v43, v43, v44
	v_mov_b32_e32 v44, v43
	s_nop 1
	v_permlane32_swap_b32_e32 v43, v44
	v_add_f32_e32 v43, v43, v44
	s_and_saveexec_b64 s[36:37], s[6:7]
	s_cbranch_execz .LBB0_378
	v_fmamk_f32 v43, v43, 0x3b2aaaab, v193
	v_mul_f32_e32 v44, 0x4f800000, v43
	v_cmp_gt_f32_e32 vcc, s67, v43
	s_nop 1
	v_cndmask_b32_e32 v43, v43, v44, vcc
	v_sqrt_f32_e32 v44, v43
	s_nop 0
	v_add_u32_e32 v45, -1, v44
	v_fma_f32 v47, -v45, v44, v43
	v_add_u32_e32 v46, 1, v44
	v_cmp_ge_f32_e64 s[2:3], 0, v47
	s_nop 1
	v_cndmask_b32_e64 v45, v44, v45, s[2:3]
	v_fma_f32 v44, -v46, v44, v43
	v_cmp_lt_f32_e64 s[2:3], 0, v44
	s_nop 1
	v_cndmask_b32_e64 v44, v45, v46, s[2:3]
	v_mul_f32_e32 v45, 0x37800000, v44
	v_cndmask_b32_e32 v44, v44, v45, vcc
	v_cmp_class_f32_e32 vcc, v43, v195
	s_nop 1
	v_cndmask_b32_e32 v43, v44, v43, vcc
	v_div_scale_f32 v44, s[0:1], v43, v43, 1.0
	v_rcp_f32_e32 v45, v44
	s_nop 0
	v_fma_f32 v46, -v44, v45, 1.0
	v_fmac_f32_e32 v45, v46, v45
	v_div_scale_f32 v46, vcc, 1.0, v43, 1.0
	v_mul_f32_e32 v47, v46, v45
	v_fma_f32 v48, -v44, v47, v46
	v_fmac_f32_e32 v47, v48, v45
	v_fma_f32 v44, -v44, v47, v46
	v_div_fmas_f32 v44, v44, v45, v47
	v_div_fixup_f32 v44, v44, v43, 1.0
	v_pk_mul_f32 v[20:21], v[20:21], v[44:45] op_sel_hi:[1,0]
	v_pk_mul_f32 v[22:23], v[22:23], v[44:45] op_sel_hi:[1,0]
	v_pk_mul_f32 v[16:17], v[16:17], v[44:45] op_sel_hi:[1,0]
	v_pk_mul_f32 v[20:21], v[4:5], v[20:21]
	v_pk_mul_f32 v[22:23], v[6:7], v[22:23]
	v_pk_mul_f32 v[16:17], v[0:1], v[16:17]
	v_cvt_pk_bf16_f32 v20, v20, v21
	v_cvt_pk_bf16_f32 v21, v22, v23
	v_cvt_pk_bf16_f32 v22, v16, v17
	v_pk_mul_f32 v[16:17], v[18:19], v[44:45] op_sel_hi:[1,0]
	s_nop 0
	v_pk_mul_f32 v[16:17], v[2:3], v[16:17]
	s_nop 0
	v_cvt_pk_bf16_f32 v23, v16, v17
	v_lshl_add_u64 v[16:17], s[14:15], 0, v[24:25]
	global_store_dwordx4 v[16:17], v[20:23], off
.LBB0_378:
	s_or_b64 exec, exec, s[36:37]
	v_pk_mul_f32 v[16:17], v[14:15], v[14:15]
	v_pk_mul_f32 v[18:19], v[12:13], v[12:13]
	s_cmpk_gt_i32 s12, 0x7fff
	v_pk_mov_b32 v[20:21], v[18:19], v[16:17] op_sel:[1,0]
	v_mov_b32_e32 v19, v17
	v_pk_add_f32 v[16:17], v[20:21], v[18:19]
	s_nop 0
	v_add_f32_e32 v16, v16, v17
	s_nop 4
	s_nop 1
	v_add_f32_dpp v16, v16, v16 quad_perm:[1,0,3,2] row_mask:0xf bank_mask:0xf
	s_nop 1
	v_add_f32_dpp v16, v16, v16 quad_perm:[2,3,0,1] row_mask:0xf bank_mask:0xf
	s_nop 1
	v_add_f32_dpp v16, v16, v16 row_half_mirror row_mask:0xf bank_mask:0xf
	s_nop 1
	v_add_f32_dpp v16, v16, v16 row_mirror row_mask:0xf bank_mask:0xf
	v_mov_b32_e32 v17, v16
	s_nop 1
	v_permlane16_swap_b32_e32 v16, v17
	v_add_f32_e32 v16, v16, v17
	v_mov_b32_e32 v17, v16
	s_nop 1
	v_permlane32_swap_b32_e32 v16, v17
	v_add_f32_e32 v16, v16, v17
	v_fmamk_f32 v16, v16, 0x3b800000, v193
	v_cmp_gt_f32_e32 vcc, s67, v16
	v_mul_f32_e32 v17, 0x4f800000, v16
	s_nop 0
	v_cndmask_b32_e32 v16, v16, v17, vcc
	v_sqrt_f32_e32 v17, v16
	s_nop 0
	v_add_u32_e32 v18, -1, v17
	v_fma_f32 v19, -v18, v17, v16
	v_cmp_ge_f32_e64 s[2:3], 0, v19
	v_add_u32_e32 v19, 1, v17
	s_nop 0
	v_cndmask_b32_e64 v18, v17, v18, s[2:3]
	v_fma_f32 v17, -v19, v17, v16
	v_cmp_lt_f32_e64 s[2:3], 0, v17
	s_nop 1
	v_cndmask_b32_e64 v17, v18, v19, s[2:3]
	v_mul_f32_e32 v18, 0x37800000, v17
	v_cndmask_b32_e32 v17, v17, v18, vcc
	v_cmp_class_f32_e32 vcc, v16, v195
	s_nop 1
	v_cndmask_b32_e32 v16, v17, v16, vcc
	v_div_scale_f32 v17, s[0:1], v16, v16, 1.0
	v_rcp_f32_e32 v18, v17
	s_nop 0
	v_fma_f32 v19, -v17, v18, 1.0
	v_fmac_f32_e32 v18, v19, v18
	v_div_scale_f32 v19, vcc, 1.0, v16, 1.0
	v_mul_f32_e32 v20, v19, v18
	v_fma_f32 v21, -v17, v20, v19
	v_fmac_f32_e32 v20, v21, v18
	v_fma_f32 v17, -v17, v20, v19
	v_div_fmas_f32 v17, v17, v18, v20
	v_div_fixup_f32 v16, v17, v16, 1.0
	v_pk_mul_f32 v[12:13], v[12:13], v[16:17] op_sel_hi:[1,0]
	v_pk_mul_f32 v[14:15], v[14:15], v[16:17] op_sel_hi:[1,0]
	v_pk_mul_f32 v[12:13], v[8:9], v[12:13]
	v_pk_mul_f32 v[14:15], v[10:11], v[14:15]
	v_cvt_pk_bf16_f32 v12, v12, v13
	v_cvt_pk_bf16_f32 v13, v14, v15
	v_lshl_add_u64 v[14:15], s[14:15], 0, v[28:29]
	global_store_dwordx2 v[14:15], v[12:13], off
	v_mov_b32_e32 v12, v49
	ds_bpermute_b32 v13, v40, v12
	s_cbranch_scc1 .LBB0_373
	v_mov_b32_e32 v14, v54
	v_mov_b32_e32 v15, v55
	s_waitcnt lgkmcnt(0)
	v_mul_f32_e32 v13, v15, v13
	v_cndmask_b32_e64 v13, v13, -v13, s[10:11]
	v_fmac_f32_e32 v13, v12, v14
	v_mov_b32_e32 v12, v13
	s_branch .LBB0_373
